# P0 x->A row loop hand-scheduled: gain vector held in registers, all 8 row loads issued together, two rows in flight
# baseline (speedup 1.0000x reference)
; __device__ __forceinline__ unsigned pk2(float lo, float hi) { unsigned r; asm volatile("v_cvt_pk_bf16_f32 %0, %1, %2" : "=v"(r) : "v"(lo), "v"(hi)); return r; }
; __device__ __forceinline__ float dot4(f32x4 v) { return (v[0] * v[0] + v[1] * v[1]) + (v[2] * v[2] + v[3] * v[3]); }
; #define KIN(i) (*(const float* const __attribute__((address_space(4)))*)(kp + 8 * (i)))
; __global__ void __launch_bounds__(NTHREADS, 2) fwd_megakernel(Args args) {
;     ...
;         for (int row = gw; row < T; row += NGW) {
;             const float* xrow = row < TP ? KIN(0) + (size_t)row * D : KIN(1) + (size_t)(row - TP) * D;
;             const f32x4* xr = (const f32x4*)xrow + lane; const f32x4* gr = (const f32x4*)KIN(3) + lane;
;             unsigned long long* o8 = (unsigned long long*)(Abuf + (size_t)row * D) + lane;
;             float s = 0.f;
; #pragma unroll
;             for (int j = 0; j < 8; ++j) { const f32x4 v = xr[64 * j]; s += dot4(v); const f32x4 o = v * gr[64 * j];
;                 o8[64 * j] = (unsigned long long)pk2(o[0], o[1]) | ((unsigned long long)pk2(o[2], o[3]) << 32); }
;             s = wave_sum(s);
;             if (lane == 0) SS[row] = s;
;         }
.LBB0_12:
	s_cmpk_gt_i32 s16, 0x47ff
	s_cbranch_scc1 .LBB0_21
	s_load_dwordx2 s[4:5], s[10:11], 0x18
	s_load_dwordx2 s[12:13], s[10:11], 0x0
	s_load_dwordx2 s[16:17], s[10:11], 0x8
	v_mov_b32_e32 v7, 0
	v_lshlrev_b32_e32 v6, 4, v2
	v_mov_b32_e32 v5, v7
	v_lshl_add_u64 v[8:9], s[8:9], 0, v[4:5]
	s_mov_b64 s[18:19], 0x990c000
	v_lshl_add_u64 v[8:9], v[8:9], 0, s[18:19]
	s_add_i32 s14, s3, s93
	v_mbcnt_lo_u32_b32 v18, -1, 0
	v_mbcnt_hi_u32_b32 v18, -1, v18
	v_xor_b32_e32 v160, 1, v18
	v_lshlrev_b32_e32 v160, 2, v160
	v_xor_b32_e32 v161, 2, v18
	v_lshlrev_b32_e32 v161, 2, v161
	v_xor_b32_e32 v162, 4, v18
	v_lshlrev_b32_e32 v162, 2, v162
	v_xor_b32_e32 v163, 8, v18
	v_lshlrev_b32_e32 v163, 2, v163
	v_xor_b32_e32 v164, 16, v18
	v_lshlrev_b32_e32 v164, 2, v164
	v_xor_b32_e32 v165, 32, v18
	v_lshlrev_b32_e32 v165, 2, v165
	s_waitcnt lgkmcnt(0)
	v_lshl_add_u64 v[10:11], s[4:5], 0, v[6:7]
	s_mov_b64 s[18:19], 0x1000
	v_lshl_add_u64 v[12:13], v[10:11], 0, s[18:19]
	global_load_dwordx4 v[64:67], v[10:11], off
	global_load_dwordx4 v[68:71], v[10:11], off offset:1024
	global_load_dwordx4 v[72:75], v[10:11], off offset:2048
	global_load_dwordx4 v[76:79], v[10:11], off offset:3072
	global_load_dwordx4 v[80:83], v[12:13], off
	global_load_dwordx4 v[84:87], v[12:13], off offset:1024
	global_load_dwordx4 v[88:91], v[12:13], off offset:2048
	global_load_dwordx4 v[92:95], v[12:13], off offset:3072
	v_cmp_eq_u32_e64 s[4:5], 0, v2
	s_cmpk_gt_i32 s14, 0x3fff
	s_cselect_b32 s28, s16, s12
	s_cselect_b32 s29, s17, s13
	s_cselect_b32 s3, 0x4000, 0
	s_sub_i32 s3, s14, s3
	s_lshl_b32 s3, s3, 13
	s_add_u32 s28, s28, s3
	s_addc_u32 s29, s29, 0
	s_add_u32 s30, s28, 0x1000
	s_addc_u32 s31, s29, 0
	s_mov_b32 s20, s14
	global_load_dwordx4 v[96:99], v6, s[28:29]
	global_load_dwordx4 v[100:103], v6, s[28:29] offset:1024
	global_load_dwordx4 v[104:107], v6, s[28:29] offset:2048
	global_load_dwordx4 v[108:111], v6, s[28:29] offset:3072
	global_load_dwordx4 v[112:115], v6, s[30:31]
	global_load_dwordx4 v[116:119], v6, s[30:31] offset:1024
	global_load_dwordx4 v[120:123], v6, s[30:31] offset:2048
	global_load_dwordx4 v[124:127], v6, s[30:31] offset:3072
	s_add_i32 s14, s14, s24
	s_cmpk_gt_i32 s14, 0x47ff
	s_cbranch_scc1 .Lp0r_tail_a
	s_cmpk_gt_i32 s14, 0x3fff
	s_cselect_b32 s28, s16, s12
	s_cselect_b32 s29, s17, s13
	s_cselect_b32 s3, 0x4000, 0
	s_sub_i32 s3, s14, s3
	s_lshl_b32 s3, s3, 13
	s_add_u32 s28, s28, s3
	s_addc_u32 s29, s29, 0
	s_add_u32 s30, s28, 0x1000
	s_addc_u32 s31, s29, 0
	s_mov_b32 s21, s14
	global_load_dwordx4 v[128:131], v6, s[28:29]
	global_load_dwordx4 v[132:135], v6, s[28:29] offset:1024
	global_load_dwordx4 v[136:139], v6, s[28:29] offset:2048
	global_load_dwordx4 v[140:143], v6, s[28:29] offset:3072
	global_load_dwordx4 v[144:147], v6, s[30:31]
	global_load_dwordx4 v[148:151], v6, s[30:31] offset:1024
	global_load_dwordx4 v[152:155], v6, s[30:31] offset:2048
	global_load_dwordx4 v[156:159], v6, s[30:31] offset:3072
	s_waitcnt vmcnt(8)
	s_lshl_b32 s18, s20, 12
	s_mov_b32 s19, 0
	v_lshl_add_u64 v[2:3], v[8:9], 0, s[18:19]
	v_mul_f32_e32 v27, v97, v97
	v_mul_f32_e32 v28, v99, v99
	v_fmac_f32_e32 v27, v96, v96
	v_fmac_f32_e32 v28, v98, v98
	v_add_f32_e32 v26, v27, v28
	v_pk_mul_f32 v[96:97], v[96:97], v[64:65]
	v_pk_mul_f32 v[98:99], v[98:99], v[66:67]
	v_cvt_pk_bf16_f32 v30, v96, v97
	v_cvt_pk_bf16_f32 v31, v98, v99
	global_store_dwordx2 v[2:3], v[30:31], off
	v_mul_f32_e32 v27, v101, v101
	v_mul_f32_e32 v28, v103, v103
	v_fmac_f32_e32 v27, v100, v100
	v_fmac_f32_e32 v28, v102, v102
	v_add_f32_e32 v27, v27, v28
	v_add_f32_e32 v26, v26, v27
	v_pk_mul_f32 v[100:101], v[100:101], v[68:69]
	v_pk_mul_f32 v[102:103], v[102:103], v[70:71]
	v_cvt_pk_bf16_f32 v32, v100, v101
	v_cvt_pk_bf16_f32 v33, v102, v103
	global_store_dwordx2 v[2:3], v[32:33], off offset:512
	v_mul_f32_e32 v27, v105, v105
	v_mul_f32_e32 v28, v107, v107
	v_fmac_f32_e32 v27, v104, v104
	v_fmac_f32_e32 v28, v106, v106
	v_add_f32_e32 v27, v27, v28
	v_add_f32_e32 v26, v26, v27
	v_pk_mul_f32 v[104:105], v[104:105], v[72:73]
	v_pk_mul_f32 v[106:107], v[106:107], v[74:75]
	v_cvt_pk_bf16_f32 v30, v104, v105
	v_cvt_pk_bf16_f32 v31, v106, v107
	global_store_dwordx2 v[2:3], v[30:31], off offset:1024
	v_mul_f32_e32 v27, v109, v109
	v_mul_f32_e32 v28, v111, v111
	v_fmac_f32_e32 v27, v108, v108
	v_fmac_f32_e32 v28, v110, v110
	v_add_f32_e32 v27, v27, v28
	v_add_f32_e32 v26, v26, v27
	v_pk_mul_f32 v[108:109], v[108:109], v[76:77]
	v_pk_mul_f32 v[110:111], v[110:111], v[78:79]
	v_cvt_pk_bf16_f32 v32, v108, v109
	v_cvt_pk_bf16_f32 v33, v110, v111
	global_store_dwordx2 v[2:3], v[32:33], off offset:1536
	v_mul_f32_e32 v27, v113, v113
	v_mul_f32_e32 v28, v115, v115
	v_fmac_f32_e32 v27, v112, v112
	v_fmac_f32_e32 v28, v114, v114
	v_add_f32_e32 v27, v27, v28
	v_add_f32_e32 v26, v26, v27
	v_pk_mul_f32 v[112:113], v[112:113], v[80:81]
	v_pk_mul_f32 v[114:115], v[114:115], v[82:83]
	v_cvt_pk_bf16_f32 v30, v112, v113
	v_cvt_pk_bf16_f32 v31, v114, v115
	global_store_dwordx2 v[2:3], v[30:31], off offset:2048
	v_mul_f32_e32 v27, v117, v117
	v_mul_f32_e32 v28, v119, v119
	v_fmac_f32_e32 v27, v116, v116
	v_fmac_f32_e32 v28, v118, v118
	v_add_f32_e32 v27, v27, v28
	v_add_f32_e32 v26, v26, v27
	v_pk_mul_f32 v[116:117], v[116:117], v[84:85]
	v_pk_mul_f32 v[118:119], v[118:119], v[86:87]
	v_cvt_pk_bf16_f32 v32, v116, v117
	v_cvt_pk_bf16_f32 v33, v118, v119
	global_store_dwordx2 v[2:3], v[32:33], off offset:2560
	v_mul_f32_e32 v27, v121, v121
	v_mul_f32_e32 v28, v123, v123
	v_fmac_f32_e32 v27, v120, v120
	v_fmac_f32_e32 v28, v122, v122
	v_add_f32_e32 v27, v27, v28
	v_add_f32_e32 v26, v26, v27
	v_pk_mul_f32 v[120:121], v[120:121], v[88:89]
	v_pk_mul_f32 v[122:123], v[122:123], v[90:91]
	v_cvt_pk_bf16_f32 v30, v120, v121
	v_cvt_pk_bf16_f32 v31, v122, v123
	global_store_dwordx2 v[2:3], v[30:31], off offset:3072
	v_mul_f32_e32 v27, v125, v125
	v_mul_f32_e32 v28, v127, v127
	v_fmac_f32_e32 v27, v124, v124
	v_fmac_f32_e32 v28, v126, v126
	v_add_f32_e32 v27, v27, v28
	v_add_f32_e32 v26, v26, v27
	v_pk_mul_f32 v[124:125], v[124:125], v[92:93]
	v_pk_mul_f32 v[126:127], v[126:127], v[94:95]
	v_cvt_pk_bf16_f32 v32, v124, v125
	v_cvt_pk_bf16_f32 v33, v126, v127
	global_store_dwordx2 v[2:3], v[32:33], off offset:3584
	ds_bpermute_b32 v27, v160, v26
	s_waitcnt lgkmcnt(0)
	v_add_f32_e32 v26, v26, v27
	ds_bpermute_b32 v27, v161, v26
	s_waitcnt lgkmcnt(0)
	v_add_f32_e32 v26, v26, v27
	ds_bpermute_b32 v27, v162, v26
	s_waitcnt lgkmcnt(0)
	v_add_f32_e32 v26, v26, v27
	ds_bpermute_b32 v27, v163, v26
	s_waitcnt lgkmcnt(0)
	v_add_f32_e32 v26, v26, v27
	ds_bpermute_b32 v27, v164, v26
	s_waitcnt lgkmcnt(0)
	v_add_f32_e32 v26, v26, v27
	ds_bpermute_b32 v27, v165, v26
	s_waitcnt lgkmcnt(0)
	v_add_f32_e32 v26, v26, v27
	s_lshl_b32 s18, s20, 2
	s_add_u32 s18, s8, s18
	s_addc_u32 s19, s9, 0
	s_and_saveexec_b64 s[22:23], s[4:5]
	global_store_dword v7, v26, s[18:19]
	s_or_b64 exec, exec, s[22:23]
; __device__ __forceinline__ unsigned pk2(float lo, float hi) { unsigned r; asm volatile("v_cvt_pk_bf16_f32 %0, %1, %2" : "=v"(r) : "v"(lo), "v"(hi)); return r; }
; __device__ __forceinline__ float dot4(f32x4 v) { return (v[0] * v[0] + v[1] * v[1]) + (v[2] * v[2] + v[3] * v[3]); }
; #define KIN(i) (*(const float* const __attribute__((address_space(4)))*)(kp + 8 * (i)))
; __global__ void __launch_bounds__(NTHREADS, 2) fwd_megakernel(Args args) {
;     ...
;         for (int row = gw; row < T; row += NGW) {
;             const float* xrow = row < TP ? KIN(0) + (size_t)row * D : KIN(1) + (size_t)(row - TP) * D;
;             const f32x4* xr = (const f32x4*)xrow + lane; const f32x4* gr = (const f32x4*)KIN(3) + lane;
;             unsigned long long* o8 = (unsigned long long*)(Abuf + (size_t)row * D) + lane;
;             float s = 0.f;
; #pragma unroll
;             for (int j = 0; j < 8; ++j) { const f32x4 v = xr[64 * j]; s += dot4(v); const f32x4 o = v * gr[64 * j];
;                 o8[64 * j] = (unsigned long long)pk2(o[0], o[1]) | ((unsigned long long)pk2(o[2], o[3]) << 32); }
;             s = wave_sum(s);
;             if (lane == 0) SS[row] = s;
.Lp0r_loop:
	s_add_i32 s14, s14, s24
	s_cmpk_gt_i32 s14, 0x47ff
	s_cbranch_scc1 .Lp0r_tail_b
	s_cmpk_gt_i32 s14, 0x3fff
	s_cselect_b32 s28, s16, s12
	s_cselect_b32 s29, s17, s13
	s_cselect_b32 s3, 0x4000, 0
	s_sub_i32 s3, s14, s3
	s_lshl_b32 s3, s3, 13
	s_add_u32 s28, s28, s3
	s_addc_u32 s29, s29, 0
	s_add_u32 s30, s28, 0x1000
	s_addc_u32 s31, s29, 0
	s_mov_b32 s20, s14
	global_load_dwordx4 v[96:99], v6, s[28:29]
	global_load_dwordx4 v[100:103], v6, s[28:29] offset:1024
	global_load_dwordx4 v[104:107], v6, s[28:29] offset:2048
	global_load_dwordx4 v[108:111], v6, s[28:29] offset:3072
	global_load_dwordx4 v[112:115], v6, s[30:31]
	global_load_dwordx4 v[116:119], v6, s[30:31] offset:1024
	global_load_dwordx4 v[120:123], v6, s[30:31] offset:2048
	global_load_dwordx4 v[124:127], v6, s[30:31] offset:3072
	s_waitcnt vmcnt(17)
	s_lshl_b32 s18, s21, 12
	s_mov_b32 s19, 0
	v_lshl_add_u64 v[2:3], v[8:9], 0, s[18:19]
	v_mul_f32_e32 v27, v129, v129
	v_mul_f32_e32 v28, v131, v131
	v_fmac_f32_e32 v27, v128, v128
	v_fmac_f32_e32 v28, v130, v130
	v_add_f32_e32 v26, v27, v28
	v_pk_mul_f32 v[128:129], v[128:129], v[64:65]
	v_pk_mul_f32 v[130:131], v[130:131], v[66:67]
	v_cvt_pk_bf16_f32 v30, v128, v129
	v_cvt_pk_bf16_f32 v31, v130, v131
	global_store_dwordx2 v[2:3], v[30:31], off
	v_mul_f32_e32 v27, v133, v133
	v_mul_f32_e32 v28, v135, v135
	v_fmac_f32_e32 v27, v132, v132
	v_fmac_f32_e32 v28, v134, v134
	v_add_f32_e32 v27, v27, v28
	v_add_f32_e32 v26, v26, v27
	v_pk_mul_f32 v[132:133], v[132:133], v[68:69]
	v_pk_mul_f32 v[134:135], v[134:135], v[70:71]
	v_cvt_pk_bf16_f32 v32, v132, v133
	v_cvt_pk_bf16_f32 v33, v134, v135
	global_store_dwordx2 v[2:3], v[32:33], off offset:512
	v_mul_f32_e32 v27, v137, v137
	v_mul_f32_e32 v28, v139, v139
	v_fmac_f32_e32 v27, v136, v136
	v_fmac_f32_e32 v28, v138, v138
	v_add_f32_e32 v27, v27, v28
	v_add_f32_e32 v26, v26, v27
	v_pk_mul_f32 v[136:137], v[136:137], v[72:73]
	v_pk_mul_f32 v[138:139], v[138:139], v[74:75]
	v_cvt_pk_bf16_f32 v30, v136, v137
	v_cvt_pk_bf16_f32 v31, v138, v139
	global_store_dwordx2 v[2:3], v[30:31], off offset:1024
	v_mul_f32_e32 v27, v141, v141
	v_mul_f32_e32 v28, v143, v143
	v_fmac_f32_e32 v27, v140, v140
	v_fmac_f32_e32 v28, v142, v142
	v_add_f32_e32 v27, v27, v28
	v_add_f32_e32 v26, v26, v27
	v_pk_mul_f32 v[140:141], v[140:141], v[76:77]
	v_pk_mul_f32 v[142:143], v[142:143], v[78:79]
	v_cvt_pk_bf16_f32 v32, v140, v141
	v_cvt_pk_bf16_f32 v33, v142, v143
	global_store_dwordx2 v[2:3], v[32:33], off offset:1536
	v_mul_f32_e32 v27, v145, v145
	v_mul_f32_e32 v28, v147, v147
	v_fmac_f32_e32 v27, v144, v144
	v_fmac_f32_e32 v28, v146, v146
	v_add_f32_e32 v27, v27, v28
	v_add_f32_e32 v26, v26, v27
	v_pk_mul_f32 v[144:145], v[144:145], v[80:81]
	v_pk_mul_f32 v[146:147], v[146:147], v[82:83]
	v_cvt_pk_bf16_f32 v30, v144, v145
	v_cvt_pk_bf16_f32 v31, v146, v147
	global_store_dwordx2 v[2:3], v[30:31], off offset:2048
	v_mul_f32_e32 v27, v149, v149
	v_mul_f32_e32 v28, v151, v151
	v_fmac_f32_e32 v27, v148, v148
	v_fmac_f32_e32 v28, v150, v150
	v_add_f32_e32 v27, v27, v28
	v_add_f32_e32 v26, v26, v27
	v_pk_mul_f32 v[148:149], v[148:149], v[84:85]
	v_pk_mul_f32 v[150:151], v[150:151], v[86:87]
	v_cvt_pk_bf16_f32 v32, v148, v149
	v_cvt_pk_bf16_f32 v33, v150, v151
	global_store_dwordx2 v[2:3], v[32:33], off offset:2560
	v_mul_f32_e32 v27, v153, v153
	v_mul_f32_e32 v28, v155, v155
	v_fmac_f32_e32 v27, v152, v152
	v_fmac_f32_e32 v28, v154, v154
	v_add_f32_e32 v27, v27, v28
	v_add_f32_e32 v26, v26, v27
	v_pk_mul_f32 v[152:153], v[152:153], v[88:89]
	v_pk_mul_f32 v[154:155], v[154:155], v[90:91]
	v_cvt_pk_bf16_f32 v30, v152, v153
	v_cvt_pk_bf16_f32 v31, v154, v155
	global_store_dwordx2 v[2:3], v[30:31], off offset:3072
	v_mul_f32_e32 v27, v157, v157
	v_mul_f32_e32 v28, v159, v159
	v_fmac_f32_e32 v27, v156, v156
	v_fmac_f32_e32 v28, v158, v158
	v_add_f32_e32 v27, v27, v28
	v_add_f32_e32 v26, v26, v27
	v_pk_mul_f32 v[156:157], v[156:157], v[92:93]
	v_pk_mul_f32 v[158:159], v[158:159], v[94:95]
	v_cvt_pk_bf16_f32 v32, v156, v157
	v_cvt_pk_bf16_f32 v33, v158, v159
	global_store_dwordx2 v[2:3], v[32:33], off offset:3584
	ds_bpermute_b32 v27, v160, v26
	s_waitcnt lgkmcnt(0)
	v_add_f32_e32 v26, v26, v27
	ds_bpermute_b32 v27, v161, v26
	s_waitcnt lgkmcnt(0)
	v_add_f32_e32 v26, v26, v27
	ds_bpermute_b32 v27, v162, v26
	s_waitcnt lgkmcnt(0)
	v_add_f32_e32 v26, v26, v27
	ds_bpermute_b32 v27, v163, v26
	s_waitcnt lgkmcnt(0)
	v_add_f32_e32 v26, v26, v27
	ds_bpermute_b32 v27, v164, v26
	s_waitcnt lgkmcnt(0)
	v_add_f32_e32 v26, v26, v27
	ds_bpermute_b32 v27, v165, v26
	s_waitcnt lgkmcnt(0)
	v_add_f32_e32 v26, v26, v27
	s_lshl_b32 s18, s21, 2
	s_add_u32 s18, s8, s18
	s_addc_u32 s19, s9, 0
	s_and_saveexec_b64 s[22:23], s[4:5]
	global_store_dword v7, v26, s[18:19]
	s_or_b64 exec, exec, s[22:23]
	s_add_i32 s14, s14, s24
	s_cmpk_gt_i32 s14, 0x47ff
	s_cbranch_scc1 .Lp0r_tail_a
; __device__ __forceinline__ unsigned pk2(float lo, float hi) { unsigned r; asm volatile("v_cvt_pk_bf16_f32 %0, %1, %2" : "=v"(r) : "v"(lo), "v"(hi)); return r; }
; __device__ __forceinline__ float dot4(f32x4 v) { return (v[0] * v[0] + v[1] * v[1]) + (v[2] * v[2] + v[3] * v[3]); }
; #define KIN(i) (*(const float* const __attribute__((address_space(4)))*)(kp + 8 * (i)))
; __global__ void __launch_bounds__(NTHREADS, 2) fwd_megakernel(Args args) {
;     ...
;         for (int row = gw; row < T; row += NGW) {
;             const float* xrow = row < TP ? KIN(0) + (size_t)row * D : KIN(1) + (size_t)(row - TP) * D;
;             const f32x4* xr = (const f32x4*)xrow + lane; const f32x4* gr = (const f32x4*)KIN(3) + lane;
;             unsigned long long* o8 = (unsigned long long*)(Abuf + (size_t)row * D) + lane;
;             float s = 0.f;
; #pragma unroll
;             for (int j = 0; j < 8; ++j) { const f32x4 v = xr[64 * j]; s += dot4(v); const f32x4 o = v * gr[64 * j];
;                 o8[64 * j] = (unsigned long long)pk2(o[0], o[1]) | ((unsigned long long)pk2(o[2], o[3]) << 32); }
;             s = wave_sum(s);
;             if (lane == 0) SS[row] = s;
	s_cmpk_gt_i32 s14, 0x3fff
	s_cselect_b32 s28, s16, s12
	s_cselect_b32 s29, s17, s13
	s_cselect_b32 s3, 0x4000, 0
	s_sub_i32 s3, s14, s3
	s_lshl_b32 s3, s3, 13
	s_add_u32 s28, s28, s3
	s_addc_u32 s29, s29, 0
	s_add_u32 s30, s28, 0x1000
	s_addc_u32 s31, s29, 0
	s_mov_b32 s21, s14
	global_load_dwordx4 v[128:131], v6, s[28:29]
	global_load_dwordx4 v[132:135], v6, s[28:29] offset:1024
	global_load_dwordx4 v[136:139], v6, s[28:29] offset:2048
	global_load_dwordx4 v[140:143], v6, s[28:29] offset:3072
	global_load_dwordx4 v[144:147], v6, s[30:31]
	global_load_dwordx4 v[148:151], v6, s[30:31] offset:1024
	global_load_dwordx4 v[152:155], v6, s[30:31] offset:2048
	global_load_dwordx4 v[156:159], v6, s[30:31] offset:3072
	s_waitcnt vmcnt(17)
	s_lshl_b32 s18, s20, 12
	s_mov_b32 s19, 0
	v_lshl_add_u64 v[2:3], v[8:9], 0, s[18:19]
	v_mul_f32_e32 v27, v97, v97
	v_mul_f32_e32 v28, v99, v99
	v_fmac_f32_e32 v27, v96, v96
	v_fmac_f32_e32 v28, v98, v98
	v_add_f32_e32 v26, v27, v28
	v_pk_mul_f32 v[96:97], v[96:97], v[64:65]
	v_pk_mul_f32 v[98:99], v[98:99], v[66:67]
	v_cvt_pk_bf16_f32 v30, v96, v97
	v_cvt_pk_bf16_f32 v31, v98, v99
	global_store_dwordx2 v[2:3], v[30:31], off
	v_mul_f32_e32 v27, v101, v101
	v_mul_f32_e32 v28, v103, v103
	v_fmac_f32_e32 v27, v100, v100
	v_fmac_f32_e32 v28, v102, v102
	v_add_f32_e32 v27, v27, v28
	v_add_f32_e32 v26, v26, v27
	v_pk_mul_f32 v[100:101], v[100:101], v[68:69]
	v_pk_mul_f32 v[102:103], v[102:103], v[70:71]
	v_cvt_pk_bf16_f32 v32, v100, v101
	v_cvt_pk_bf16_f32 v33, v102, v103
	global_store_dwordx2 v[2:3], v[32:33], off offset:512
	v_mul_f32_e32 v27, v105, v105
	v_mul_f32_e32 v28, v107, v107
	v_fmac_f32_e32 v27, v104, v104
	v_fmac_f32_e32 v28, v106, v106
	v_add_f32_e32 v27, v27, v28
	v_add_f32_e32 v26, v26, v27
	v_pk_mul_f32 v[104:105], v[104:105], v[72:73]
	v_pk_mul_f32 v[106:107], v[106:107], v[74:75]
	v_cvt_pk_bf16_f32 v30, v104, v105
	v_cvt_pk_bf16_f32 v31, v106, v107
	global_store_dwordx2 v[2:3], v[30:31], off offset:1024
	v_mul_f32_e32 v27, v109, v109
	v_mul_f32_e32 v28, v111, v111
	v_fmac_f32_e32 v27, v108, v108
	v_fmac_f32_e32 v28, v110, v110
	v_add_f32_e32 v27, v27, v28
	v_add_f32_e32 v26, v26, v27
	v_pk_mul_f32 v[108:109], v[108:109], v[76:77]
	v_pk_mul_f32 v[110:111], v[110:111], v[78:79]
	v_cvt_pk_bf16_f32 v32, v108, v109
	v_cvt_pk_bf16_f32 v33, v110, v111
	global_store_dwordx2 v[2:3], v[32:33], off offset:1536
	v_mul_f32_e32 v27, v113, v113
	v_mul_f32_e32 v28, v115, v115
	v_fmac_f32_e32 v27, v112, v112
	v_fmac_f32_e32 v28, v114, v114
	v_add_f32_e32 v27, v27, v28
	v_add_f32_e32 v26, v26, v27
	v_pk_mul_f32 v[112:113], v[112:113], v[80:81]
	v_pk_mul_f32 v[114:115], v[114:115], v[82:83]
	v_cvt_pk_bf16_f32 v30, v112, v113
	v_cvt_pk_bf16_f32 v31, v114, v115
	global_store_dwordx2 v[2:3], v[30:31], off offset:2048
	v_mul_f32_e32 v27, v117, v117
	v_mul_f32_e32 v28, v119, v119
	v_fmac_f32_e32 v27, v116, v116
	v_fmac_f32_e32 v28, v118, v118
	v_add_f32_e32 v27, v27, v28
	v_add_f32_e32 v26, v26, v27
	v_pk_mul_f32 v[116:117], v[116:117], v[84:85]
	v_pk_mul_f32 v[118:119], v[118:119], v[86:87]
	v_cvt_pk_bf16_f32 v32, v116, v117
	v_cvt_pk_bf16_f32 v33, v118, v119
	global_store_dwordx2 v[2:3], v[32:33], off offset:2560
	v_mul_f32_e32 v27, v121, v121
	v_mul_f32_e32 v28, v123, v123
	v_fmac_f32_e32 v27, v120, v120
	v_fmac_f32_e32 v28, v122, v122
	v_add_f32_e32 v27, v27, v28
	v_add_f32_e32 v26, v26, v27
	v_pk_mul_f32 v[120:121], v[120:121], v[88:89]
	v_pk_mul_f32 v[122:123], v[122:123], v[90:91]
	v_cvt_pk_bf16_f32 v30, v120, v121
	v_cvt_pk_bf16_f32 v31, v122, v123
	global_store_dwordx2 v[2:3], v[30:31], off offset:3072
	v_mul_f32_e32 v27, v125, v125
	v_mul_f32_e32 v28, v127, v127
	v_fmac_f32_e32 v27, v124, v124
	v_fmac_f32_e32 v28, v126, v126
	v_add_f32_e32 v27, v27, v28
	v_add_f32_e32 v26, v26, v27
	v_pk_mul_f32 v[124:125], v[124:125], v[92:93]
	v_pk_mul_f32 v[126:127], v[126:127], v[94:95]
	v_cvt_pk_bf16_f32 v32, v124, v125
	v_cvt_pk_bf16_f32 v33, v126, v127
	global_store_dwordx2 v[2:3], v[32:33], off offset:3584
	ds_bpermute_b32 v27, v160, v26
	s_waitcnt lgkmcnt(0)
	v_add_f32_e32 v26, v26, v27
	ds_bpermute_b32 v27, v161, v26
	s_waitcnt lgkmcnt(0)
	v_add_f32_e32 v26, v26, v27
	ds_bpermute_b32 v27, v162, v26
	s_waitcnt lgkmcnt(0)
	v_add_f32_e32 v26, v26, v27
	ds_bpermute_b32 v27, v163, v26
	s_waitcnt lgkmcnt(0)
	v_add_f32_e32 v26, v26, v27
	ds_bpermute_b32 v27, v164, v26
	s_waitcnt lgkmcnt(0)
	v_add_f32_e32 v26, v26, v27
	ds_bpermute_b32 v27, v165, v26
	s_waitcnt lgkmcnt(0)
	v_add_f32_e32 v26, v26, v27
	s_lshl_b32 s18, s20, 2
	s_add_u32 s18, s8, s18
	s_addc_u32 s19, s9, 0
	s_and_saveexec_b64 s[22:23], s[4:5]
	global_store_dword v7, v26, s[18:19]
	s_or_b64 exec, exec, s[22:23]
	s_branch .Lp0r_loop
; __device__ __forceinline__ unsigned pk2(float lo, float hi) { unsigned r; asm volatile("v_cvt_pk_bf16_f32 %0, %1, %2" : "=v"(r) : "v"(lo), "v"(hi)); return r; }
; __device__ __forceinline__ float dot4(f32x4 v) { return (v[0] * v[0] + v[1] * v[1]) + (v[2] * v[2] + v[3] * v[3]); }
; #define KIN(i) (*(const float* const __attribute__((address_space(4)))*)(kp + 8 * (i)))
; __global__ void __launch_bounds__(NTHREADS, 2) fwd_megakernel(Args args) {
;     ...
;         for (int row = gw; row < T; row += NGW) {
;             const float* xrow = row < TP ? KIN(0) + (size_t)row * D : KIN(1) + (size_t)(row - TP) * D;
;             const f32x4* xr = (const f32x4*)xrow + lane; const f32x4* gr = (const f32x4*)KIN(3) + lane;
;             unsigned long long* o8 = (unsigned long long*)(Abuf + (size_t)row * D) + lane;
;             float s = 0.f;
; #pragma unroll
;             for (int j = 0; j < 8; ++j) { const f32x4 v = xr[64 * j]; s += dot4(v); const f32x4 o = v * gr[64 * j];
;                 o8[64 * j] = (unsigned long long)pk2(o[0], o[1]) | ((unsigned long long)pk2(o[2], o[3]) << 32); }
;             s = wave_sum(s);
;             if (lane == 0) SS[row] = s;
.Lp0r_tail_a:
	s_waitcnt vmcnt(0)
	s_lshl_b32 s18, s20, 12
	s_mov_b32 s19, 0
	v_lshl_add_u64 v[2:3], v[8:9], 0, s[18:19]
	v_mul_f32_e32 v27, v97, v97
	v_mul_f32_e32 v28, v99, v99
	v_fmac_f32_e32 v27, v96, v96
	v_fmac_f32_e32 v28, v98, v98
	v_add_f32_e32 v26, v27, v28
	v_pk_mul_f32 v[96:97], v[96:97], v[64:65]
	v_pk_mul_f32 v[98:99], v[98:99], v[66:67]
	v_cvt_pk_bf16_f32 v30, v96, v97
	v_cvt_pk_bf16_f32 v31, v98, v99
	global_store_dwordx2 v[2:3], v[30:31], off
	v_mul_f32_e32 v27, v101, v101
	v_mul_f32_e32 v28, v103, v103
	v_fmac_f32_e32 v27, v100, v100
	v_fmac_f32_e32 v28, v102, v102
	v_add_f32_e32 v27, v27, v28
	v_add_f32_e32 v26, v26, v27
	v_pk_mul_f32 v[100:101], v[100:101], v[68:69]
	v_pk_mul_f32 v[102:103], v[102:103], v[70:71]
	v_cvt_pk_bf16_f32 v32, v100, v101
	v_cvt_pk_bf16_f32 v33, v102, v103
	global_store_dwordx2 v[2:3], v[32:33], off offset:512
	v_mul_f32_e32 v27, v105, v105
	v_mul_f32_e32 v28, v107, v107
	v_fmac_f32_e32 v27, v104, v104
	v_fmac_f32_e32 v28, v106, v106
	v_add_f32_e32 v27, v27, v28
	v_add_f32_e32 v26, v26, v27
	v_pk_mul_f32 v[104:105], v[104:105], v[72:73]
	v_pk_mul_f32 v[106:107], v[106:107], v[74:75]
	v_cvt_pk_bf16_f32 v30, v104, v105
	v_cvt_pk_bf16_f32 v31, v106, v107
	global_store_dwordx2 v[2:3], v[30:31], off offset:1024
	v_mul_f32_e32 v27, v109, v109
	v_mul_f32_e32 v28, v111, v111
	v_fmac_f32_e32 v27, v108, v108
	v_fmac_f32_e32 v28, v110, v110
	v_add_f32_e32 v27, v27, v28
	v_add_f32_e32 v26, v26, v27
	v_pk_mul_f32 v[108:109], v[108:109], v[76:77]
	v_pk_mul_f32 v[110:111], v[110:111], v[78:79]
	v_cvt_pk_bf16_f32 v32, v108, v109
	v_cvt_pk_bf16_f32 v33, v110, v111
	global_store_dwordx2 v[2:3], v[32:33], off offset:1536
	v_mul_f32_e32 v27, v113, v113
	v_mul_f32_e32 v28, v115, v115
	v_fmac_f32_e32 v27, v112, v112
	v_fmac_f32_e32 v28, v114, v114
	v_add_f32_e32 v27, v27, v28
	v_add_f32_e32 v26, v26, v27
	v_pk_mul_f32 v[112:113], v[112:113], v[80:81]
	v_pk_mul_f32 v[114:115], v[114:115], v[82:83]
	v_cvt_pk_bf16_f32 v30, v112, v113
	v_cvt_pk_bf16_f32 v31, v114, v115
	global_store_dwordx2 v[2:3], v[30:31], off offset:2048
	v_mul_f32_e32 v27, v117, v117
	v_mul_f32_e32 v28, v119, v119
	v_fmac_f32_e32 v27, v116, v116
	v_fmac_f32_e32 v28, v118, v118
	v_add_f32_e32 v27, v27, v28
	v_add_f32_e32 v26, v26, v27
	v_pk_mul_f32 v[116:117], v[116:117], v[84:85]
	v_pk_mul_f32 v[118:119], v[118:119], v[86:87]
	v_cvt_pk_bf16_f32 v32, v116, v117
	v_cvt_pk_bf16_f32 v33, v118, v119
	global_store_dwordx2 v[2:3], v[32:33], off offset:2560
	v_mul_f32_e32 v27, v121, v121
	v_mul_f32_e32 v28, v123, v123
	v_fmac_f32_e32 v27, v120, v120
	v_fmac_f32_e32 v28, v122, v122
	v_add_f32_e32 v27, v27, v28
	v_add_f32_e32 v26, v26, v27
	v_pk_mul_f32 v[120:121], v[120:121], v[88:89]
	v_pk_mul_f32 v[122:123], v[122:123], v[90:91]
	v_cvt_pk_bf16_f32 v30, v120, v121
	v_cvt_pk_bf16_f32 v31, v122, v123
	global_store_dwordx2 v[2:3], v[30:31], off offset:3072
	v_mul_f32_e32 v27, v125, v125
	v_mul_f32_e32 v28, v127, v127
	v_fmac_f32_e32 v27, v124, v124
	v_fmac_f32_e32 v28, v126, v126
	v_add_f32_e32 v27, v27, v28
	v_add_f32_e32 v26, v26, v27
	v_pk_mul_f32 v[124:125], v[124:125], v[92:93]
	v_pk_mul_f32 v[126:127], v[126:127], v[94:95]
	v_cvt_pk_bf16_f32 v32, v124, v125
	v_cvt_pk_bf16_f32 v33, v126, v127
	global_store_dwordx2 v[2:3], v[32:33], off offset:3584
	ds_bpermute_b32 v27, v160, v26
	s_waitcnt lgkmcnt(0)
	v_add_f32_e32 v26, v26, v27
	ds_bpermute_b32 v27, v161, v26
	s_waitcnt lgkmcnt(0)
	v_add_f32_e32 v26, v26, v27
	ds_bpermute_b32 v27, v162, v26
	s_waitcnt lgkmcnt(0)
	v_add_f32_e32 v26, v26, v27
	ds_bpermute_b32 v27, v163, v26
	s_waitcnt lgkmcnt(0)
	v_add_f32_e32 v26, v26, v27
	ds_bpermute_b32 v27, v164, v26
	s_waitcnt lgkmcnt(0)
	v_add_f32_e32 v26, v26, v27
	ds_bpermute_b32 v27, v165, v26
	s_waitcnt lgkmcnt(0)
	v_add_f32_e32 v26, v26, v27
	s_lshl_b32 s18, s20, 2
	s_add_u32 s18, s8, s18
	s_addc_u32 s19, s9, 0
	s_and_saveexec_b64 s[22:23], s[4:5]
	global_store_dword v7, v26, s[18:19]
	s_or_b64 exec, exec, s[22:23]
	s_branch .LBB0_21
; __device__ __forceinline__ unsigned pk2(float lo, float hi) { unsigned r; asm volatile("v_cvt_pk_bf16_f32 %0, %1, %2" : "=v"(r) : "v"(lo), "v"(hi)); return r; }
; __device__ __forceinline__ float dot4(f32x4 v) { return (v[0] * v[0] + v[1] * v[1]) + (v[2] * v[2] + v[3] * v[3]); }
; #define KIN(i) (*(const float* const __attribute__((address_space(4)))*)(kp + 8 * (i)))
; __global__ void __launch_bounds__(NTHREADS, 2) fwd_megakernel(Args args) {
;     ...
;         for (int row = gw; row < T; row += NGW) {
;             const float* xrow = row < TP ? KIN(0) + (size_t)row * D : KIN(1) + (size_t)(row - TP) * D;
;             const f32x4* xr = (const f32x4*)xrow + lane; const f32x4* gr = (const f32x4*)KIN(3) + lane;
;             unsigned long long* o8 = (unsigned long long*)(Abuf + (size_t)row * D) + lane;
;             float s = 0.f;
; #pragma unroll
;             for (int j = 0; j < 8; ++j) { const f32x4 v = xr[64 * j]; s += dot4(v); const f32x4 o = v * gr[64 * j];
;                 o8[64 * j] = (unsigned long long)pk2(o[0], o[1]) | ((unsigned long long)pk2(o[2], o[3]) << 32); }
;             s = wave_sum(s);
;             if (lane == 0) SS[row] = s;
.Lp0r_tail_b:
	s_waitcnt vmcnt(0)
	s_lshl_b32 s18, s21, 12
	s_mov_b32 s19, 0
	v_lshl_add_u64 v[2:3], v[8:9], 0, s[18:19]
	v_mul_f32_e32 v27, v129, v129
	v_mul_f32_e32 v28, v131, v131
	v_fmac_f32_e32 v27, v128, v128
	v_fmac_f32_e32 v28, v130, v130
	v_add_f32_e32 v26, v27, v28
	v_pk_mul_f32 v[128:129], v[128:129], v[64:65]
	v_pk_mul_f32 v[130:131], v[130:131], v[66:67]
	v_cvt_pk_bf16_f32 v30, v128, v129
	v_cvt_pk_bf16_f32 v31, v130, v131
	global_store_dwordx2 v[2:3], v[30:31], off
	v_mul_f32_e32 v27, v133, v133
	v_mul_f32_e32 v28, v135, v135
	v_fmac_f32_e32 v27, v132, v132
	v_fmac_f32_e32 v28, v134, v134
	v_add_f32_e32 v27, v27, v28
	v_add_f32_e32 v26, v26, v27
	v_pk_mul_f32 v[132:133], v[132:133], v[68:69]
	v_pk_mul_f32 v[134:135], v[134:135], v[70:71]
	v_cvt_pk_bf16_f32 v32, v132, v133
	v_cvt_pk_bf16_f32 v33, v134, v135
	global_store_dwordx2 v[2:3], v[32:33], off offset:512
	v_mul_f32_e32 v27, v137, v137
	v_mul_f32_e32 v28, v139, v139
	v_fmac_f32_e32 v27, v136, v136
	v_fmac_f32_e32 v28, v138, v138
	v_add_f32_e32 v27, v27, v28
	v_add_f32_e32 v26, v26, v27
	v_pk_mul_f32 v[136:137], v[136:137], v[72:73]
	v_pk_mul_f32 v[138:139], v[138:139], v[74:75]
	v_cvt_pk_bf16_f32 v30, v136, v137
	v_cvt_pk_bf16_f32 v31, v138, v139
	global_store_dwordx2 v[2:3], v[30:31], off offset:1024
	v_mul_f32_e32 v27, v141, v141
	v_mul_f32_e32 v28, v143, v143
	v_fmac_f32_e32 v27, v140, v140
	v_fmac_f32_e32 v28, v142, v142
	v_add_f32_e32 v27, v27, v28
	v_add_f32_e32 v26, v26, v27
	v_pk_mul_f32 v[140:141], v[140:141], v[76:77]
	v_pk_mul_f32 v[142:143], v[142:143], v[78:79]
	v_cvt_pk_bf16_f32 v32, v140, v141
	v_cvt_pk_bf16_f32 v33, v142, v143
	global_store_dwordx2 v[2:3], v[32:33], off offset:1536
	v_mul_f32_e32 v27, v145, v145
	v_mul_f32_e32 v28, v147, v147
	v_fmac_f32_e32 v27, v144, v144
	v_fmac_f32_e32 v28, v146, v146
	v_add_f32_e32 v27, v27, v28
	v_add_f32_e32 v26, v26, v27
	v_pk_mul_f32 v[144:145], v[144:145], v[80:81]
	v_pk_mul_f32 v[146:147], v[146:147], v[82:83]
	v_cvt_pk_bf16_f32 v30, v144, v145
	v_cvt_pk_bf16_f32 v31, v146, v147
	global_store_dwordx2 v[2:3], v[30:31], off offset:2048
	v_mul_f32_e32 v27, v149, v149
	v_mul_f32_e32 v28, v151, v151
	v_fmac_f32_e32 v27, v148, v148
	v_fmac_f32_e32 v28, v150, v150
	v_add_f32_e32 v27, v27, v28
	v_add_f32_e32 v26, v26, v27
	v_pk_mul_f32 v[148:149], v[148:149], v[84:85]
	v_pk_mul_f32 v[150:151], v[150:151], v[86:87]
	v_cvt_pk_bf16_f32 v32, v148, v149
	v_cvt_pk_bf16_f32 v33, v150, v151
	global_store_dwordx2 v[2:3], v[32:33], off offset:2560
	v_mul_f32_e32 v27, v153, v153
	v_mul_f32_e32 v28, v155, v155
	v_fmac_f32_e32 v27, v152, v152
	v_fmac_f32_e32 v28, v154, v154
	v_add_f32_e32 v27, v27, v28
	v_add_f32_e32 v26, v26, v27
	v_pk_mul_f32 v[152:153], v[152:153], v[88:89]
	v_pk_mul_f32 v[154:155], v[154:155], v[90:91]
	v_cvt_pk_bf16_f32 v30, v152, v153
	v_cvt_pk_bf16_f32 v31, v154, v155
	global_store_dwordx2 v[2:3], v[30:31], off offset:3072
	v_mul_f32_e32 v27, v157, v157
	v_mul_f32_e32 v28, v159, v159
	v_fmac_f32_e32 v27, v156, v156
	v_fmac_f32_e32 v28, v158, v158
	v_add_f32_e32 v27, v27, v28
	v_add_f32_e32 v26, v26, v27
	v_pk_mul_f32 v[156:157], v[156:157], v[92:93]
	v_pk_mul_f32 v[158:159], v[158:159], v[94:95]
	v_cvt_pk_bf16_f32 v32, v156, v157
	v_cvt_pk_bf16_f32 v33, v158, v159
	global_store_dwordx2 v[2:3], v[32:33], off offset:3584
	ds_bpermute_b32 v27, v160, v26
	s_waitcnt lgkmcnt(0)
	v_add_f32_e32 v26, v26, v27
	ds_bpermute_b32 v27, v161, v26
	s_waitcnt lgkmcnt(0)
	v_add_f32_e32 v26, v26, v27
	ds_bpermute_b32 v27, v162, v26
	s_waitcnt lgkmcnt(0)
	v_add_f32_e32 v26, v26, v27
	ds_bpermute_b32 v27, v163, v26
	s_waitcnt lgkmcnt(0)
	v_add_f32_e32 v26, v26, v27
	ds_bpermute_b32 v27, v164, v26
	s_waitcnt lgkmcnt(0)
	v_add_f32_e32 v26, v26, v27
	ds_bpermute_b32 v27, v165, v26
	s_waitcnt lgkmcnt(0)
	v_add_f32_e32 v26, v26, v27
	s_lshl_b32 s18, s21, 2
	s_add_u32 s18, s8, s18
	s_addc_u32 s19, s9, 0
	s_and_saveexec_b64 s[22:23], s[4:5]
	global_store_dword v7, v26, s[18:19]
	s_or_b64 exec, exec, s[22:23]
